# combo on v12: early next-unit stats loads + all epilogue bpermutes hoisted (regs v234-253) + cvt-chain redundant LDS waits removed
# speedup vs baseline: 1.0103x; 1.0103x over previous
.Lup_sig_skip:
	v_mbcnt_lo_u32_b32 v177, -1, 0
	v_mbcnt_hi_u32_b32 v177, -1, v177
	s_lshl_b32 s3, s3, 11
	v_and_b32_e32 v180, 15, v177
	v_ashrrev_i32_e32 v183, 4, v177
	s_add_i32 s3, s53, s3
	v_lshlrev_b32_e32 v181, 2, v180
	ds_bpermute_b32 v182, v181, v176
	ds_bpermute_b32 v184, v181, v179
	ds_bpermute_b32 v202, v181, v179 offset:64
	ds_bpermute_b32 v204, v181, v176 offset:64
	ds_bpermute_b32 v206, v181, v179 offset:128
	ds_bpermute_b32 v208, v181, v176 offset:128
	ds_bpermute_b32 v210, v181, v179 offset:192
	ds_bpermute_b32 v212, v181, v176 offset:192
	ds_bpermute_b32 v234, v181, v174
	ds_bpermute_b32 v236, v181, v175
	ds_bpermute_b32 v238, v181, v175 offset:64
	ds_bpermute_b32 v240, v181, v174 offset:64
	ds_bpermute_b32 v244, v181, v175 offset:128
	ds_bpermute_b32 v248, v181, v174 offset:128
	ds_bpermute_b32 v250, v181, v175 offset:192
	ds_bpermute_b32 v252, v181, v174 offset:192
	v_lshl_add_u32 v114, v183, 5, s3
	ds_read_b128 v[142:145], v114
	ds_read_b128 v[122:125], v114 offset:16
	ds_read_b128 v[146:149], v114 offset:1024
	ds_read_b128 v[126:129], v114 offset:1040
	ds_read_b128 v[138:141], v114 offset:512
	ds_read_b128 v[110:113], v114 offset:528
	ds_read_b128 v[134:137], v114 offset:1536
	ds_read_b128 v[114:117], v114 offset:1552
	s_lshl_b32 s23, s36, 7
	s_waitcnt lgkmcnt(0)
	v_pk_fma_f32 v[158:159], v[142:143], v[182:183], v[158:159] op_sel_hi:[1,0,1] neg_lo:[1,0,0] neg_hi:[1,0,0]
	v_pk_fma_f32 v[160:161], v[144:145], v[182:183], v[160:161] op_sel_hi:[1,0,1] neg_lo:[1,0,0] neg_hi:[1,0,0]
	v_pk_fma_f32 v[198:199], v[158:159], v[184:185], v[146:147] op_sel_hi:[1,0,1]
	s_or_b32 s23, s23, s49
	v_mul_f32_e32 v158, 0xbfb8aa3b, v198
	v_exp_f32_e32 v158, v158
	v_mul_f32_e32 v159, 0xbfb8aa3b, v199
	v_exp_f32_e32 v159, v159
	v_pk_fma_f32 v[160:161], v[160:161], v[184:185], v[148:149] op_sel_hi:[1,0,1]
	v_add_f32_e32 v158, 1.0, v158
	v_lshl_add_u32 v196, v183, 3, s23
	v_rcp_f32_e32 v200, v158
	v_add_f32_e32 v158, 1.0, v159
	v_pk_fma_f32 v[154:155], v[138:139], v[182:183], v[154:155] op_sel_hi:[1,0,1] neg_lo:[1,0,0] neg_hi:[1,0,0]
	v_mul_f32_e32 v183, 0xbfb8aa3b, v160
	v_rcp_f32_e32 v201, v158
	v_pk_fma_f32 v[154:155], v[154:155], v[184:185], v[134:135] op_sel_hi:[1,0,1]
	v_exp_f32_e32 v183, v183
	v_mul_f32_e32 v185, 0xbfb8aa3b, v161
	v_exp_f32_e32 v185, v185
	v_ashrrev_i32_e32 v197, 31, v196
	v_lshl_add_u64 v[158:159], v[196:197], 1, s[92:93]
	v_pk_mul_f32 v[196:197], v[198:199], v[200:201]
	v_add_f32_e32 v183, 1.0, v183
	v_pk_mul_f32 v[154:155], v[154:155], v[196:197]
	v_rcp_f32_e32 v196, v183
	v_pk_fma_f32 v[156:157], v[140:141], v[182:183], v[156:157] op_sel_hi:[1,0,1] neg_lo:[1,0,0] neg_hi:[1,0,0]
	v_add_f32_e32 v183, 1.0, v185
	v_rcp_f32_e32 v197, v183
	v_pk_fma_f32 v[150:151], v[122:123], v[182:183], v[150:151] op_sel_hi:[1,0,1] neg_lo:[1,0,0] neg_hi:[1,0,0]
	v_pk_fma_f32 v[156:157], v[156:157], v[184:185], v[136:137] op_sel_hi:[1,0,1]
	v_pk_fma_f32 v[150:151], v[150:151], v[184:185], v[126:127] op_sel_hi:[1,0,1]
	v_pk_mul_f32 v[160:161], v[160:161], v[196:197]
	v_mul_f32_e32 v183, 0xbfb8aa3b, v150
	v_exp_f32_e32 v183, v183
	v_pk_mul_f32 v[156:157], v[156:157], v[160:161]
	v_mul_f32_e32 v161, 0xbfb8aa3b, v151
	v_exp_f32_e32 v161, v161
	v_pk_fma_f32 v[152:153], v[124:125], v[182:183], v[152:153] op_sel_hi:[1,0,1] neg_lo:[1,0,0] neg_hi:[1,0,0]
	v_pk_fma_f32 v[130:131], v[110:111], v[182:183], v[130:131] op_sel_hi:[1,0,1] neg_lo:[1,0,0] neg_hi:[1,0,0]
	v_pk_fma_f32 v[152:153], v[152:153], v[184:185], v[128:129] op_sel_hi:[1,0,1]
	v_add_f32_e32 v160, 1.0, v183
	v_pk_fma_f32 v[130:131], v[130:131], v[184:185], v[114:115] op_sel_hi:[1,0,1]
	v_add_f32_e32 v161, 1.0, v161
	v_mul_f32_e32 v183, 0xbfb8aa3b, v152
	v_mul_f32_e32 v185, 0xbfb8aa3b, v153
	v_rcp_f32_e32 v160, v160
	v_rcp_f32_e32 v161, v161
	v_exp_f32_e32 v183, v183
	v_exp_f32_e32 v185, v185
	s_lshl_b32 s3, s30, 8
	v_pk_mul_f32 v[150:151], v[150:151], v[160:161]
	v_add_f32_e32 v160, 1.0, v183
	v_add_f32_e32 v161, 1.0, v185
	v_rcp_f32_e32 v160, v160
	v_rcp_f32_e32 v161, v161
	v_pk_mul_f32 v[150:151], v[130:131], v[150:151]
	v_pk_fma_f32 v[130:131], v[112:113], v[182:183], v[132:133] op_sel_hi:[1,0,1] neg_lo:[1,0,0] neg_hi:[1,0,0]
	s_add_i32 s3, s3, s45
	v_pk_fma_f32 v[130:131], v[130:131], v[184:185], v[116:117] op_sel_hi:[1,0,1]
	v_pk_mul_f32 v[132:133], v[152:153], v[160:161]
	v_pk_mul_f32 v[152:153], v[130:131], v[132:133]
	v_cvt_pk_bf16_f32 v130, v154, v155
	v_cvt_pk_bf16_f32 v132, v150, v151
	v_cvt_pk_bf16_f32 v133, v152, v153
	v_add_u32_e32 v180, s3, v180
	v_cvt_pk_bf16_f32 v131, v156, v157
	v_pk_fma_f32 v[118:119], v[142:143], v[204:205], v[118:119] op_sel_hi:[1,0,1] neg_lo:[1,0,0] neg_hi:[1,0,0]
	v_pk_fma_f32 v[106:107], v[138:139], v[204:205], v[106:107] op_sel_hi:[1,0,1] neg_lo:[1,0,0] neg_hi:[1,0,0]
	v_pk_fma_f32 v[118:119], v[118:119], v[202:203], v[146:147] op_sel_hi:[1,0,1]
	v_pk_fma_f32 v[120:121], v[144:145], v[204:205], v[120:121] op_sel_hi:[1,0,1] neg_lo:[1,0,0] neg_hi:[1,0,0]
	v_mul_f32_e32 v150, 0xbfb8aa3b, v118
	v_exp_f32_e32 v152, v150
	v_mul_f32_e32 v150, 0xbfb8aa3b, v119
	v_exp_f32_e32 v153, v150
	v_mad_i64_i32 v[150:151], s[38:39], v180, s65, v[158:159]
	v_add_f32_e32 v152, 1.0, v152
	v_add_f32_e32 v153, 1.0, v153
	v_rcp_f32_e32 v152, v152
	v_rcp_f32_e32 v153, v153
	v_pk_fma_f32 v[106:107], v[106:107], v[202:203], v[134:135] op_sel_hi:[1,0,1]
	v_pk_fma_f32 v[120:121], v[120:121], v[202:203], v[148:149] op_sel_hi:[1,0,1]
	global_store_dwordx4 v[150:151], v[130:133], off sc1
	v_pk_mul_f32 v[118:119], v[118:119], v[152:153]
	v_pk_fma_f32 v[108:109], v[140:141], v[204:205], v[108:109] op_sel_hi:[1,0,1] neg_lo:[1,0,0] neg_hi:[1,0,0]
	v_mul_f32_e32 v130, 0xbfb8aa3b, v120
	v_pk_mul_f32 v[106:107], v[106:107], v[118:119]
	v_mul_f32_e32 v118, 0xbfb8aa3b, v121
	v_exp_f32_e32 v130, v130
	v_exp_f32_e32 v119, v118
	v_pk_fma_f32 v[102:103], v[122:123], v[204:205], v[102:103] op_sel_hi:[1,0,1] neg_lo:[1,0,0] neg_hi:[1,0,0]
	v_pk_fma_f32 v[108:109], v[108:109], v[202:203], v[136:137] op_sel_hi:[1,0,1]
	v_add_f32_e32 v118, 1.0, v130
	v_add_f32_e32 v119, 1.0, v119
	v_rcp_f32_e32 v118, v118
	v_rcp_f32_e32 v119, v119
	v_pk_fma_f32 v[102:103], v[102:103], v[202:203], v[126:127] op_sel_hi:[1,0,1]
	v_pk_fma_f32 v[104:105], v[124:125], v[204:205], v[104:105] op_sel_hi:[1,0,1] neg_lo:[1,0,0] neg_hi:[1,0,0]
	v_mul_f32_e32 v130, 0xbfb8aa3b, v102
	v_pk_mul_f32 v[118:119], v[120:121], v[118:119]
	v_exp_f32_e32 v130, v130
	v_pk_mul_f32 v[108:109], v[108:109], v[118:119]
	v_mul_f32_e32 v119, 0xbfb8aa3b, v103
	v_exp_f32_e32 v119, v119
	v_pk_fma_f32 v[104:105], v[104:105], v[202:203], v[128:129] op_sel_hi:[1,0,1]
	v_add_f32_e32 v118, 1.0, v130
	v_mul_f32_e32 v120, 0xbfb8aa3b, v104
	v_add_f32_e32 v119, 1.0, v119
	v_mul_f32_e32 v121, 0xbfb8aa3b, v105
	v_rcp_f32_e32 v118, v118
	v_rcp_f32_e32 v119, v119
	v_exp_f32_e32 v120, v120
	v_exp_f32_e32 v121, v121
	v_pk_fma_f32 v[98:99], v[110:111], v[204:205], v[98:99] op_sel_hi:[1,0,1] neg_lo:[1,0,0] neg_hi:[1,0,0]
	v_pk_mul_f32 v[102:103], v[102:103], v[118:119]
	v_add_f32_e32 v118, 1.0, v120
	v_add_f32_e32 v119, 1.0, v121
	v_rcp_f32_e32 v118, v118
	v_rcp_f32_e32 v119, v119
	v_pk_fma_f32 v[98:99], v[98:99], v[202:203], v[114:115] op_sel_hi:[1,0,1]
	s_andn2_b64 vcc, exec, s[0:1]
	v_pk_mul_f32 v[102:103], v[98:99], v[102:103]
	v_pk_fma_f32 v[98:99], v[112:113], v[204:205], v[100:101] op_sel_hi:[1,0,1] neg_lo:[1,0,0] neg_hi:[1,0,0]
	v_pk_mul_f32 v[100:101], v[104:105], v[118:119]
	v_pk_fma_f32 v[98:99], v[98:99], v[202:203], v[116:117] op_sel_hi:[1,0,1]
	v_pk_mul_f32 v[104:105], v[98:99], v[100:101]
	v_cvt_pk_bf16_f32 v98, v106, v107
	v_add_u32_e32 v119, 16, v180
	v_cvt_pk_bf16_f32 v100, v102, v103
	v_cvt_pk_bf16_f32 v101, v104, v105
	v_cvt_pk_bf16_f32 v99, v108, v109
	v_pk_fma_f32 v[94:95], v[142:143], v[208:209], v[94:95] op_sel_hi:[1,0,1] neg_lo:[1,0,0] neg_hi:[1,0,0]
	v_pk_fma_f32 v[90:91], v[138:139], v[208:209], v[90:91] op_sel_hi:[1,0,1] neg_lo:[1,0,0] neg_hi:[1,0,0]
	v_pk_fma_f32 v[94:95], v[94:95], v[206:207], v[146:147] op_sel_hi:[1,0,1]
	v_pk_fma_f32 v[96:97], v[144:145], v[208:209], v[96:97] op_sel_hi:[1,0,1] neg_lo:[1,0,0] neg_hi:[1,0,0]
	v_mul_f32_e32 v102, 0xbfb8aa3b, v94
	v_exp_f32_e32 v104, v102
	v_mul_f32_e32 v102, 0xbfb8aa3b, v95
	v_exp_f32_e32 v105, v102
	v_mad_i64_i32 v[102:103], s[38:39], v119, s65, v[158:159]
	v_add_f32_e32 v104, 1.0, v104
	v_add_f32_e32 v105, 1.0, v105
	v_rcp_f32_e32 v104, v104
	v_rcp_f32_e32 v105, v105
	v_pk_fma_f32 v[90:91], v[90:91], v[206:207], v[134:135] op_sel_hi:[1,0,1]
	v_pk_fma_f32 v[96:97], v[96:97], v[206:207], v[148:149] op_sel_hi:[1,0,1]
	global_store_dwordx4 v[102:103], v[98:101], off sc1
	v_pk_mul_f32 v[94:95], v[94:95], v[104:105]
	v_pk_fma_f32 v[92:93], v[140:141], v[208:209], v[92:93] op_sel_hi:[1,0,1] neg_lo:[1,0,0] neg_hi:[1,0,0]
	v_mul_f32_e32 v98, 0xbfb8aa3b, v96
	v_pk_mul_f32 v[90:91], v[90:91], v[94:95]
	v_mul_f32_e32 v94, 0xbfb8aa3b, v97
	v_exp_f32_e32 v98, v98
	v_exp_f32_e32 v95, v94
	v_pk_fma_f32 v[86:87], v[122:123], v[208:209], v[86:87] op_sel_hi:[1,0,1] neg_lo:[1,0,0] neg_hi:[1,0,0]
	v_pk_fma_f32 v[92:93], v[92:93], v[206:207], v[136:137] op_sel_hi:[1,0,1]
	v_add_f32_e32 v94, 1.0, v98
	v_add_f32_e32 v95, 1.0, v95
	v_rcp_f32_e32 v94, v94
	v_rcp_f32_e32 v95, v95
	v_pk_fma_f32 v[86:87], v[86:87], v[206:207], v[126:127] op_sel_hi:[1,0,1]
	v_pk_fma_f32 v[88:89], v[124:125], v[208:209], v[88:89] op_sel_hi:[1,0,1] neg_lo:[1,0,0] neg_hi:[1,0,0]
	v_mul_f32_e32 v98, 0xbfb8aa3b, v86
	v_pk_mul_f32 v[94:95], v[96:97], v[94:95]
	v_exp_f32_e32 v98, v98
	v_pk_mul_f32 v[92:93], v[92:93], v[94:95]
	v_mul_f32_e32 v95, 0xbfb8aa3b, v87
	v_exp_f32_e32 v95, v95
	v_pk_fma_f32 v[88:89], v[88:89], v[206:207], v[128:129] op_sel_hi:[1,0,1]
	v_add_f32_e32 v94, 1.0, v98
	v_mul_f32_e32 v96, 0xbfb8aa3b, v88
	v_add_f32_e32 v95, 1.0, v95
	v_mul_f32_e32 v97, 0xbfb8aa3b, v89
	v_rcp_f32_e32 v94, v94
	v_rcp_f32_e32 v95, v95
	v_exp_f32_e32 v96, v96
	v_exp_f32_e32 v97, v97
	v_pk_fma_f32 v[82:83], v[110:111], v[208:209], v[82:83] op_sel_hi:[1,0,1] neg_lo:[1,0,0] neg_hi:[1,0,0]
	v_pk_mul_f32 v[86:87], v[86:87], v[94:95]
	v_add_f32_e32 v94, 1.0, v96
	v_add_f32_e32 v95, 1.0, v97
	v_rcp_f32_e32 v94, v94
	v_rcp_f32_e32 v95, v95
	v_pk_fma_f32 v[82:83], v[82:83], v[206:207], v[114:115] op_sel_hi:[1,0,1]
	s_mov_b64 s[0:1], -1
	v_pk_mul_f32 v[86:87], v[82:83], v[86:87]
	v_pk_fma_f32 v[82:83], v[112:113], v[208:209], v[84:85] op_sel_hi:[1,0,1] neg_lo:[1,0,0] neg_hi:[1,0,0]
	v_pk_mul_f32 v[84:85], v[88:89], v[94:95]
	v_pk_fma_f32 v[82:83], v[82:83], v[206:207], v[116:117] op_sel_hi:[1,0,1]
	v_pk_mul_f32 v[88:89], v[82:83], v[84:85]
	v_cvt_pk_bf16_f32 v82, v90, v91
	v_add_u32_e32 v95, 32, v180
	v_cvt_pk_bf16_f32 v84, v86, v87
	v_cvt_pk_bf16_f32 v85, v88, v89
	v_cvt_pk_bf16_f32 v83, v92, v93
	v_pk_fma_f32 v[78:79], v[142:143], v[212:213], v[78:79] op_sel_hi:[1,0,1] neg_lo:[1,0,0] neg_hi:[1,0,0]
	v_pk_fma_f32 v[74:75], v[138:139], v[212:213], v[74:75] op_sel_hi:[1,0,1] neg_lo:[1,0,0] neg_hi:[1,0,0]
	v_pk_fma_f32 v[78:79], v[78:79], v[210:211], v[146:147] op_sel_hi:[1,0,1]
	v_pk_fma_f32 v[80:81], v[144:145], v[212:213], v[80:81] op_sel_hi:[1,0,1] neg_lo:[1,0,0] neg_hi:[1,0,0]
	v_mul_f32_e32 v86, 0xbfb8aa3b, v78
	v_exp_f32_e32 v88, v86
	v_mul_f32_e32 v86, 0xbfb8aa3b, v79
	v_exp_f32_e32 v89, v86
	v_mad_i64_i32 v[86:87], s[38:39], v95, s65, v[158:159]
	v_add_f32_e32 v88, 1.0, v88
	v_add_f32_e32 v89, 1.0, v89
	v_rcp_f32_e32 v88, v88
	v_rcp_f32_e32 v89, v89
	v_pk_fma_f32 v[74:75], v[74:75], v[210:211], v[134:135] op_sel_hi:[1,0,1]
	v_pk_fma_f32 v[80:81], v[80:81], v[210:211], v[148:149] op_sel_hi:[1,0,1]
	global_store_dwordx4 v[86:87], v[82:85], off sc1
	v_pk_mul_f32 v[78:79], v[78:79], v[88:89]
	v_pk_fma_f32 v[76:77], v[140:141], v[212:213], v[76:77] op_sel_hi:[1,0,1] neg_lo:[1,0,0] neg_hi:[1,0,0]
	v_mul_f32_e32 v82, 0xbfb8aa3b, v80
	v_pk_mul_f32 v[74:75], v[74:75], v[78:79]
	v_mul_f32_e32 v78, 0xbfb8aa3b, v81
	v_exp_f32_e32 v82, v82
	v_exp_f32_e32 v79, v78
	v_pk_fma_f32 v[70:71], v[122:123], v[212:213], v[70:71] op_sel_hi:[1,0,1] neg_lo:[1,0,0] neg_hi:[1,0,0]
	v_pk_fma_f32 v[76:77], v[76:77], v[210:211], v[136:137] op_sel_hi:[1,0,1]
	v_add_f32_e32 v78, 1.0, v82
	v_add_f32_e32 v79, 1.0, v79
	v_rcp_f32_e32 v78, v78
	v_rcp_f32_e32 v79, v79
	v_pk_fma_f32 v[70:71], v[70:71], v[210:211], v[126:127] op_sel_hi:[1,0,1]
	v_pk_fma_f32 v[72:73], v[124:125], v[212:213], v[72:73] op_sel_hi:[1,0,1] neg_lo:[1,0,0] neg_hi:[1,0,0]
	v_mul_f32_e32 v82, 0xbfb8aa3b, v70
	v_pk_mul_f32 v[78:79], v[80:81], v[78:79]
	v_exp_f32_e32 v82, v82
	v_pk_mul_f32 v[76:77], v[76:77], v[78:79]
	v_mul_f32_e32 v79, 0xbfb8aa3b, v71
	v_exp_f32_e32 v79, v79
	v_pk_fma_f32 v[72:73], v[72:73], v[210:211], v[128:129] op_sel_hi:[1,0,1]
	v_add_f32_e32 v78, 1.0, v82
	v_mul_f32_e32 v80, 0xbfb8aa3b, v72
	v_add_f32_e32 v79, 1.0, v79
	v_mul_f32_e32 v81, 0xbfb8aa3b, v73
	v_rcp_f32_e32 v78, v78
	v_rcp_f32_e32 v79, v79
	v_exp_f32_e32 v80, v80
	v_exp_f32_e32 v81, v81
	v_pk_fma_f32 v[66:67], v[110:111], v[212:213], v[66:67] op_sel_hi:[1,0,1] neg_lo:[1,0,0] neg_hi:[1,0,0]
	v_pk_mul_f32 v[70:71], v[70:71], v[78:79]
	v_add_f32_e32 v78, 1.0, v80
	v_add_f32_e32 v79, 1.0, v81
	v_rcp_f32_e32 v78, v78
	v_rcp_f32_e32 v79, v79
	v_pk_fma_f32 v[66:67], v[66:67], v[210:211], v[114:115] op_sel_hi:[1,0,1]
	s_nop 0
	v_pk_mul_f32 v[70:71], v[66:67], v[70:71]
	v_pk_fma_f32 v[66:67], v[112:113], v[212:213], v[68:69] op_sel_hi:[1,0,1] neg_lo:[1,0,0] neg_hi:[1,0,0]
	v_pk_mul_f32 v[68:69], v[72:73], v[78:79]
	v_pk_fma_f32 v[66:67], v[66:67], v[210:211], v[116:117] op_sel_hi:[1,0,1]
	v_add_u32_e32 v78, 48, v180
	v_pk_mul_f32 v[72:73], v[66:67], v[68:69]
	v_cvt_pk_bf16_f32 v68, v70, v71
	v_cvt_pk_bf16_f32 v66, v74, v75
	v_cvt_pk_bf16_f32 v67, v76, v77
	v_cvt_pk_bf16_f32 v69, v72, v73
	v_pk_fma_f32 v[62:63], v[142:143], v[234:235], v[62:63] op_sel_hi:[1,0,1] neg_lo:[1,0,0] neg_hi:[1,0,0]
	v_mad_i64_i32 v[72:73], s[38:39], v78, s65, v[158:159]
	v_pk_fma_f32 v[62:63], v[62:63], v[236:237], v[146:147] op_sel_hi:[1,0,1]
	global_store_dwordx4 v[72:73], v[66:69], off sc1
	s_cbranch_vccnz .Lup_stats_skip
	s_lshl_b32 s0, s22, 8
	s_add_i32 s0, s0, s45
	v_add_u32_e32 v232, s0, v177
	v_ashrrev_i32_e32 v233, 31, v232
	v_lshlrev_b64 v[228:229], 7, v[232:233]
	v_add_u32_e32 v232, 0x80, v232
	v_ashrrev_i32_e32 v233, 31, v232
	v_lshlrev_b64 v[230:231], 7, v[232:233]
	v_lshl_add_u64 v[228:229], s[94:95], 0, v[228:229]
	v_lshl_add_u64 v[230:231], s[94:95], 0, v[230:231]
	global_load_dwordx4 v[224:227], v[228:229], off
	global_load_dwordx4 v[216:219], v[228:229], off offset:16
	global_load_dwordx4 v[212:215], v[228:229], off offset:32
	global_load_dwordx4 v[208:211], v[228:229], off offset:48
	global_load_dwordx4 v[204:207], v[228:229], off offset:64
	global_load_dwordx4 v[200:203], v[228:229], off offset:80
	global_load_dwordx4 v[196:199], v[228:229], off offset:96
	global_load_dwordx4 v[154:157], v[228:229], off offset:112
	global_load_dwordx4 v[150:153], v[230:231], off
	global_load_dwordx4 v[130:133], v[230:231], off offset:16
	global_load_dwordx4 v[118:121], v[230:231], off offset:32
	global_load_dwordx4 v[104:107], v[230:231], off offset:48
	global_load_dwordx4 v[100:103], v[230:231], off offset:64
	global_load_dwordx4 v[96:99], v[230:231], off offset:80
	global_load_dwordx4 v[92:95], v[230:231], off offset:96
	global_load_dwordx4 v[88:91], v[230:231], off offset:112
.Lup_stats_skip:
	v_mul_f32_e32 v71, 0xbfb8aa3b, v62
	v_mul_f32_e32 v75, 0xbfb8aa3b, v63
	v_exp_f32_e32 v71, v71
	v_exp_f32_e32 v75, v75
	v_add_u32_e32 v68, 0x80, v180
	v_add_f32_e32 v66, 1.0, v71
	v_add_f32_e32 v67, 1.0, v75
	v_rcp_f32_e32 v66, v66
	v_rcp_f32_e32 v67, v67
	v_pk_fma_f32 v[58:59], v[138:139], v[234:235], v[58:59] op_sel_hi:[1,0,1] neg_lo:[1,0,0] neg_hi:[1,0,0]
	v_pk_fma_f32 v[64:65], v[144:145], v[234:235], v[64:65] op_sel_hi:[1,0,1] neg_lo:[1,0,0] neg_hi:[1,0,0]
	v_pk_fma_f32 v[58:59], v[58:59], v[236:237], v[134:135] op_sel_hi:[1,0,1]
	v_pk_mul_f32 v[62:63], v[62:63], v[66:67]
	v_pk_fma_f32 v[64:65], v[64:65], v[236:237], v[148:149] op_sel_hi:[1,0,1]
	v_pk_mul_f32 v[58:59], v[58:59], v[62:63]
	v_mul_f32_e32 v66, 0xbfb8aa3b, v64
	v_mul_f32_e32 v62, 0xbfb8aa3b, v65
	v_exp_f32_e32 v66, v66
	v_exp_f32_e32 v63, v62
	v_pk_fma_f32 v[60:61], v[140:141], v[234:235], v[60:61] op_sel_hi:[1,0,1] neg_lo:[1,0,0] neg_hi:[1,0,0]
	v_pk_fma_f32 v[54:55], v[122:123], v[234:235], v[54:55] op_sel_hi:[1,0,1] neg_lo:[1,0,0] neg_hi:[1,0,0]
	v_add_f32_e32 v62, 1.0, v66
	v_add_f32_e32 v63, 1.0, v63
	v_rcp_f32_e32 v62, v62
	v_rcp_f32_e32 v63, v63
	v_pk_fma_f32 v[54:55], v[54:55], v[236:237], v[126:127] op_sel_hi:[1,0,1]
	v_pk_fma_f32 v[60:61], v[60:61], v[236:237], v[136:137] op_sel_hi:[1,0,1]
	v_mul_f32_e32 v66, 0xbfb8aa3b, v54
	v_pk_mul_f32 v[62:63], v[64:65], v[62:63]
	v_exp_f32_e32 v66, v66
	v_pk_mul_f32 v[60:61], v[60:61], v[62:63]
	v_mul_f32_e32 v63, 0xbfb8aa3b, v55
	v_exp_f32_e32 v63, v63
	v_pk_fma_f32 v[56:57], v[124:125], v[234:235], v[56:57] op_sel_hi:[1,0,1] neg_lo:[1,0,0] neg_hi:[1,0,0]
	v_add_f32_e32 v62, 1.0, v66
	v_pk_fma_f32 v[56:57], v[56:57], v[236:237], v[128:129] op_sel_hi:[1,0,1]
	v_add_f32_e32 v63, 1.0, v63
	v_mul_f32_e32 v64, 0xbfb8aa3b, v56
	v_mul_f32_e32 v65, 0xbfb8aa3b, v57
	v_rcp_f32_e32 v62, v62
	v_rcp_f32_e32 v63, v63
	v_exp_f32_e32 v64, v64
	v_exp_f32_e32 v65, v65
	v_pk_fma_f32 v[50:51], v[110:111], v[234:235], v[50:51] op_sel_hi:[1,0,1] neg_lo:[1,0,0] neg_hi:[1,0,0]
	v_pk_mul_f32 v[54:55], v[54:55], v[62:63]
	v_add_f32_e32 v62, 1.0, v64
	v_add_f32_e32 v63, 1.0, v65
	v_rcp_f32_e32 v62, v62
	v_rcp_f32_e32 v63, v63
	v_pk_fma_f32 v[50:51], v[50:51], v[236:237], v[114:115] op_sel_hi:[1,0,1]
	s_nop 0
	v_pk_mul_f32 v[54:55], v[50:51], v[54:55]
	v_pk_fma_f32 v[50:51], v[112:113], v[234:235], v[52:53] op_sel_hi:[1,0,1] neg_lo:[1,0,0] neg_hi:[1,0,0]
	v_pk_mul_f32 v[52:53], v[56:57], v[62:63]
	v_pk_fma_f32 v[50:51], v[50:51], v[236:237], v[116:117] op_sel_hi:[1,0,1]
	v_pk_mul_f32 v[56:57], v[50:51], v[52:53]
	v_cvt_pk_bf16_f32 v50, v58, v59
	v_cvt_pk_bf16_f32 v52, v54, v55
	v_cvt_pk_bf16_f32 v53, v56, v57
	v_cvt_pk_bf16_f32 v51, v60, v61
	v_pk_fma_f32 v[46:47], v[142:143], v[240:241], v[46:47] op_sel_hi:[1,0,1] neg_lo:[1,0,0] neg_hi:[1,0,0]
	s_nop 0
	v_pk_fma_f32 v[46:47], v[46:47], v[238:239], v[146:147] op_sel_hi:[1,0,1]
	v_pk_fma_f32 v[42:43], v[138:139], v[240:241], v[42:43] op_sel_hi:[1,0,1] neg_lo:[1,0,0] neg_hi:[1,0,0]
	v_mul_f32_e32 v54, 0xbfb8aa3b, v46
	v_exp_f32_e32 v56, v54
	v_mul_f32_e32 v54, 0xbfb8aa3b, v47
	v_exp_f32_e32 v57, v54
	v_pk_fma_f32 v[48:49], v[144:145], v[240:241], v[48:49] op_sel_hi:[1,0,1] neg_lo:[1,0,0] neg_hi:[1,0,0]
	v_add_f32_e32 v56, 1.0, v56
	v_rcp_f32_e32 v56, v56
	v_add_f32_e32 v57, 1.0, v57
	v_rcp_f32_e32 v57, v57
	v_mad_i64_i32 v[54:55], s[38:39], v68, s65, v[158:159]
	v_pk_fma_f32 v[42:43], v[42:43], v[238:239], v[134:135] op_sel_hi:[1,0,1]
	v_pk_mul_f32 v[46:47], v[46:47], v[56:57]
	v_pk_fma_f32 v[48:49], v[48:49], v[238:239], v[148:149] op_sel_hi:[1,0,1]
	global_store_dwordx4 v[54:55], v[50:53], off sc1
	v_pk_mul_f32 v[42:43], v[42:43], v[46:47]
	v_mul_f32_e32 v46, 0xbfb8aa3b, v49
	v_mul_f32_e32 v50, 0xbfb8aa3b, v48
	v_exp_f32_e32 v50, v50
	v_exp_f32_e32 v47, v46
	v_pk_fma_f32 v[44:45], v[140:141], v[240:241], v[44:45] op_sel_hi:[1,0,1] neg_lo:[1,0,0] neg_hi:[1,0,0]
	v_pk_fma_f32 v[38:39], v[122:123], v[240:241], v[38:39] op_sel_hi:[1,0,1] neg_lo:[1,0,0] neg_hi:[1,0,0]
	v_add_f32_e32 v46, 1.0, v50
	v_add_f32_e32 v47, 1.0, v47
	v_rcp_f32_e32 v46, v46
	v_rcp_f32_e32 v47, v47
	v_pk_fma_f32 v[38:39], v[38:39], v[238:239], v[126:127] op_sel_hi:[1,0,1]
	v_pk_fma_f32 v[44:45], v[44:45], v[238:239], v[136:137] op_sel_hi:[1,0,1]
	v_mul_f32_e32 v50, 0xbfb8aa3b, v38
	v_pk_mul_f32 v[46:47], v[48:49], v[46:47]
	v_exp_f32_e32 v50, v50
	v_pk_mul_f32 v[44:45], v[44:45], v[46:47]
	v_mul_f32_e32 v47, 0xbfb8aa3b, v39
	v_exp_f32_e32 v47, v47
	v_pk_fma_f32 v[40:41], v[124:125], v[240:241], v[40:41] op_sel_hi:[1,0,1] neg_lo:[1,0,0] neg_hi:[1,0,0]
	v_add_f32_e32 v46, 1.0, v50
	v_pk_fma_f32 v[40:41], v[40:41], v[238:239], v[128:129] op_sel_hi:[1,0,1]
	v_add_f32_e32 v47, 1.0, v47
	v_mul_f32_e32 v48, 0xbfb8aa3b, v40
	v_mul_f32_e32 v49, 0xbfb8aa3b, v41
	v_rcp_f32_e32 v46, v46
	v_rcp_f32_e32 v47, v47
	v_exp_f32_e32 v48, v48
	v_exp_f32_e32 v49, v49
	v_pk_fma_f32 v[34:35], v[110:111], v[240:241], v[34:35] op_sel_hi:[1,0,1] neg_lo:[1,0,0] neg_hi:[1,0,0]
	v_pk_mul_f32 v[38:39], v[38:39], v[46:47]
	v_add_f32_e32 v46, 1.0, v48
	v_add_f32_e32 v47, 1.0, v49
	v_rcp_f32_e32 v46, v46
	v_rcp_f32_e32 v47, v47
	v_pk_fma_f32 v[34:35], v[34:35], v[238:239], v[114:115] op_sel_hi:[1,0,1]
	s_nop 0
	v_pk_mul_f32 v[38:39], v[34:35], v[38:39]
	v_pk_fma_f32 v[34:35], v[112:113], v[240:241], v[36:37] op_sel_hi:[1,0,1] neg_lo:[1,0,0] neg_hi:[1,0,0]
	v_pk_mul_f32 v[36:37], v[40:41], v[46:47]
	v_pk_fma_f32 v[34:35], v[34:35], v[238:239], v[116:117] op_sel_hi:[1,0,1]
	v_pk_mul_f32 v[40:41], v[34:35], v[36:37]
	v_cvt_pk_bf16_f32 v34, v42, v43
	v_add_u32_e32 v47, 0x90, v180
	v_cvt_pk_bf16_f32 v36, v38, v39
	v_cvt_pk_bf16_f32 v37, v40, v41
	v_cvt_pk_bf16_f32 v35, v44, v45
	v_pk_fma_f32 v[30:31], v[142:143], v[248:249], v[30:31] op_sel_hi:[1,0,1] neg_lo:[1,0,0] neg_hi:[1,0,0]
	v_pk_fma_f32 v[26:27], v[138:139], v[248:249], v[26:27] op_sel_hi:[1,0,1] neg_lo:[1,0,0] neg_hi:[1,0,0]
	v_pk_fma_f32 v[30:31], v[30:31], v[244:245], v[146:147] op_sel_hi:[1,0,1]
	v_pk_fma_f32 v[32:33], v[144:145], v[248:249], v[32:33] op_sel_hi:[1,0,1] neg_lo:[1,0,0] neg_hi:[1,0,0]
	v_mul_f32_e32 v38, 0xbfb8aa3b, v30
	v_exp_f32_e32 v40, v38
	v_mul_f32_e32 v38, 0xbfb8aa3b, v31
	v_exp_f32_e32 v41, v38
	v_mad_i64_i32 v[38:39], s[38:39], v47, s65, v[158:159]
	v_add_f32_e32 v40, 1.0, v40
	v_add_f32_e32 v41, 1.0, v41
	v_rcp_f32_e32 v40, v40
	v_rcp_f32_e32 v41, v41
	v_pk_fma_f32 v[26:27], v[26:27], v[244:245], v[134:135] op_sel_hi:[1,0,1]
	v_pk_fma_f32 v[32:33], v[32:33], v[244:245], v[148:149] op_sel_hi:[1,0,1]
	global_store_dwordx4 v[38:39], v[34:37], off sc1
	v_pk_mul_f32 v[30:31], v[30:31], v[40:41]
	v_pk_fma_f32 v[28:29], v[140:141], v[248:249], v[28:29] op_sel_hi:[1,0,1] neg_lo:[1,0,0] neg_hi:[1,0,0]
	v_mul_f32_e32 v34, 0xbfb8aa3b, v32
	v_pk_mul_f32 v[26:27], v[26:27], v[30:31]
	v_mul_f32_e32 v30, 0xbfb8aa3b, v33
	v_exp_f32_e32 v34, v34
	v_exp_f32_e32 v31, v30
	v_pk_fma_f32 v[22:23], v[122:123], v[248:249], v[22:23] op_sel_hi:[1,0,1] neg_lo:[1,0,0] neg_hi:[1,0,0]
	v_pk_fma_f32 v[28:29], v[28:29], v[244:245], v[136:137] op_sel_hi:[1,0,1]
	v_add_f32_e32 v30, 1.0, v34
	v_add_f32_e32 v31, 1.0, v31
	v_rcp_f32_e32 v30, v30
	v_rcp_f32_e32 v31, v31
	v_pk_fma_f32 v[22:23], v[22:23], v[244:245], v[126:127] op_sel_hi:[1,0,1]
	v_pk_fma_f32 v[24:25], v[124:125], v[248:249], v[24:25] op_sel_hi:[1,0,1] neg_lo:[1,0,0] neg_hi:[1,0,0]
	v_mul_f32_e32 v34, 0xbfb8aa3b, v22
	v_pk_mul_f32 v[30:31], v[32:33], v[30:31]
	v_exp_f32_e32 v34, v34
	v_pk_mul_f32 v[28:29], v[28:29], v[30:31]
	v_mul_f32_e32 v31, 0xbfb8aa3b, v23
	v_exp_f32_e32 v31, v31
	v_pk_fma_f32 v[24:25], v[24:25], v[244:245], v[128:129] op_sel_hi:[1,0,1]
	v_add_f32_e32 v30, 1.0, v34
	v_mul_f32_e32 v32, 0xbfb8aa3b, v24
	v_add_f32_e32 v31, 1.0, v31
	v_mul_f32_e32 v33, 0xbfb8aa3b, v25
	v_rcp_f32_e32 v30, v30
	v_rcp_f32_e32 v31, v31
	v_exp_f32_e32 v32, v32
	v_exp_f32_e32 v33, v33
	v_pk_fma_f32 v[18:19], v[110:111], v[248:249], v[18:19] op_sel_hi:[1,0,1] neg_lo:[1,0,0] neg_hi:[1,0,0]
	v_pk_mul_f32 v[22:23], v[22:23], v[30:31]
	v_add_f32_e32 v30, 1.0, v32
	v_add_f32_e32 v31, 1.0, v33
	v_rcp_f32_e32 v30, v30
	v_rcp_f32_e32 v31, v31
	v_pk_fma_f32 v[18:19], v[18:19], v[244:245], v[114:115] op_sel_hi:[1,0,1]
	s_nop 0
	v_pk_mul_f32 v[22:23], v[18:19], v[22:23]
	v_pk_fma_f32 v[18:19], v[112:113], v[248:249], v[20:21] op_sel_hi:[1,0,1] neg_lo:[1,0,0] neg_hi:[1,0,0]
	v_pk_mul_f32 v[20:21], v[24:25], v[30:31]
	v_pk_fma_f32 v[18:19], v[18:19], v[244:245], v[116:117] op_sel_hi:[1,0,1]
	v_pk_mul_f32 v[24:25], v[18:19], v[20:21]
	v_cvt_pk_bf16_f32 v18, v26, v27
	v_add_u32_e32 v31, 0xa0, v180
	v_cvt_pk_bf16_f32 v20, v22, v23
	v_cvt_pk_bf16_f32 v21, v24, v25
	v_cvt_pk_bf16_f32 v19, v28, v29
	v_pk_fma_f32 v[14:15], v[142:143], v[252:253], v[14:15] op_sel_hi:[1,0,1] neg_lo:[1,0,0] neg_hi:[1,0,0]
	v_pk_fma_f32 v[10:11], v[138:139], v[252:253], v[10:11] op_sel_hi:[1,0,1] neg_lo:[1,0,0] neg_hi:[1,0,0]
	v_pk_fma_f32 v[14:15], v[14:15], v[250:251], v[146:147] op_sel_hi:[1,0,1]
	v_pk_fma_f32 v[16:17], v[144:145], v[252:253], v[16:17] op_sel_hi:[1,0,1] neg_lo:[1,0,0] neg_hi:[1,0,0]
	v_mul_f32_e32 v22, 0xbfb8aa3b, v14
	v_exp_f32_e32 v24, v22
	v_mul_f32_e32 v22, 0xbfb8aa3b, v15
	v_exp_f32_e32 v25, v22
	v_mad_i64_i32 v[22:23], s[38:39], v31, s65, v[158:159]
	v_add_f32_e32 v24, 1.0, v24
	v_add_f32_e32 v25, 1.0, v25
	v_rcp_f32_e32 v24, v24
	v_rcp_f32_e32 v25, v25
	v_pk_fma_f32 v[10:11], v[10:11], v[250:251], v[134:135] op_sel_hi:[1,0,1]
	v_pk_fma_f32 v[16:17], v[16:17], v[250:251], v[148:149] op_sel_hi:[1,0,1]
	global_store_dwordx4 v[22:23], v[18:21], off sc1
	v_pk_mul_f32 v[14:15], v[14:15], v[24:25]
	v_pk_fma_f32 v[12:13], v[140:141], v[252:253], v[12:13] op_sel_hi:[1,0,1] neg_lo:[1,0,0] neg_hi:[1,0,0]
	v_mul_f32_e32 v18, 0xbfb8aa3b, v16
	v_pk_mul_f32 v[10:11], v[10:11], v[14:15]
	v_mul_f32_e32 v14, 0xbfb8aa3b, v17
	v_exp_f32_e32 v18, v18
	v_exp_f32_e32 v15, v14
	v_pk_fma_f32 v[6:7], v[122:123], v[252:253], v[6:7] op_sel_hi:[1,0,1] neg_lo:[1,0,0] neg_hi:[1,0,0]
	v_pk_fma_f32 v[12:13], v[12:13], v[250:251], v[136:137] op_sel_hi:[1,0,1]
	v_add_f32_e32 v14, 1.0, v18
	v_add_f32_e32 v15, 1.0, v15
	v_rcp_f32_e32 v14, v14
	v_rcp_f32_e32 v15, v15
	v_pk_fma_f32 v[6:7], v[6:7], v[250:251], v[126:127] op_sel_hi:[1,0,1]
	v_pk_fma_f32 v[8:9], v[124:125], v[252:253], v[8:9] op_sel_hi:[1,0,1] neg_lo:[1,0,0] neg_hi:[1,0,0]
	v_mul_f32_e32 v18, 0xbfb8aa3b, v6
	v_pk_mul_f32 v[14:15], v[16:17], v[14:15]
	v_exp_f32_e32 v18, v18
	v_pk_mul_f32 v[12:13], v[12:13], v[14:15]
	v_mul_f32_e32 v15, 0xbfb8aa3b, v7
	v_exp_f32_e32 v15, v15
	v_pk_fma_f32 v[8:9], v[8:9], v[250:251], v[128:129] op_sel_hi:[1,0,1]
	v_add_f32_e32 v14, 1.0, v18
	v_mul_f32_e32 v16, 0xbfb8aa3b, v8
	v_add_f32_e32 v15, 1.0, v15
	v_mul_f32_e32 v17, 0xbfb8aa3b, v9
	v_rcp_f32_e32 v14, v14
	v_rcp_f32_e32 v15, v15
	v_exp_f32_e32 v16, v16
	v_exp_f32_e32 v17, v17
	v_pk_fma_f32 v[2:3], v[110:111], v[252:253], v[2:3] op_sel_hi:[1,0,1] neg_lo:[1,0,0] neg_hi:[1,0,0]
	v_pk_mul_f32 v[6:7], v[6:7], v[14:15]
	v_add_f32_e32 v14, 1.0, v16
	v_add_f32_e32 v15, 1.0, v17
	v_rcp_f32_e32 v14, v14
	v_rcp_f32_e32 v15, v15
	v_pk_fma_f32 v[2:3], v[2:3], v[250:251], v[114:115] op_sel_hi:[1,0,1]
	s_nop 0
	v_pk_mul_f32 v[6:7], v[2:3], v[6:7]
	v_pk_fma_f32 v[2:3], v[112:113], v[252:253], v[4:5] op_sel_hi:[1,0,1] neg_lo:[1,0,0] neg_hi:[1,0,0]
	v_pk_mul_f32 v[4:5], v[8:9], v[14:15]
	v_pk_fma_f32 v[2:3], v[2:3], v[250:251], v[116:117] op_sel_hi:[1,0,1]
	v_add_u32_e32 v14, 0xb0, v180
	v_pk_mul_f32 v[8:9], v[2:3], v[4:5]
	v_cvt_pk_bf16_f32 v2, v10, v11
	v_cvt_pk_bf16_f32 v3, v12, v13
	v_cvt_pk_bf16_f32 v4, v6, v7
	v_cvt_pk_bf16_f32 v5, v8, v9
	v_mad_i64_i32 v[6:7], s[38:39], v14, s65, v[158:159]
	global_store_dwordx4 v[6:7], v[2:5], off sc1
	v_writelane_b32 v255, s30, 46
	s_cbranch_vccnz .LBB0_941
	s_andn2_b64 vcc, exec, s[18:19]
	s_cbranch_vccnz .LBB0_940
	s_barrier
	s_branch .LBB0_940
